# prep queue: filter tasks and adaLN tasks alternate in queue order (DRAM streaming starts with the first round)
# speedup vs baseline: 1.0298x; 1.0093x over previous
.LBB0_1090:
	s_or_b64 exec, exec, s[10:11]
	s_mov_b64 s[10:11], src_shared_base
	s_cmp_lg_u32 s69, -1
	s_cselect_b32 s3, s69, 0
	s_cselect_b32 s10, s11, 0
	v_mov_b32_e32 v2, s3
	v_mov_b32_e32 v3, s10
	s_waitcnt lgkmcnt(0)
	s_barrier
	flat_load_dword v4, v[2:3] sc0 sc1
	s_waitcnt vmcnt(0)
	s_movk_i32 s3, 0x5b4
	s_mov_b64 s[14:15], -1
	s_waitcnt lgkmcnt(0)
	s_barrier
	v_lshrrev_b32_e32 v2, 1, v4
	v_and_b32_e32 v3, 1, v4
	v_mul_u32_u24_e32 v3, 0x140, v3
	v_cmp_gt_u32_e32 vcc, 0x280, v4
	v_add_u32_e32 v2, v2, v3
	s_nop 0
	v_cndmask_b32_e32 v4, v4, v2, vcc
	v_cmp_gt_i32_e32 vcc, s3, v4
	s_and_saveexec_b64 s[10:11], vcc
	s_cbranch_execz .LBB0_1085
	s_movk_i32 s3, 0x13f
	v_cmp_lt_i32_e32 vcc, s3, v4
	s_and_saveexec_b64 s[12:13], vcc
	s_xor_b64 s[14:15], exec, s[12:13]
	s_cbranch_execz .LBB0_1227
	s_movk_i32 s3, 0x2bf
	v_cmp_lt_u32_e32 vcc, s3, v4
	s_and_saveexec_b64 s[12:13], vcc
	s_xor_b64 s[16:17], exec, s[12:13]
	s_cbranch_execz .LBB0_1220
	s_movk_i32 s3, 0x35f
	v_cmp_lt_u32_e64 s[52:53], s3, v4
	s_movk_i32 s3, 0x364
	v_cmp_gt_u32_e64 s[54:55], s3, v4
	v_cndmask_b32_e64 v0, 0, 1, s[52:53]
	s_movk_i32 s3, 0x3a4
	v_cndmask_b32_e64 v0, 2, v0, s[54:55]
	v_cmp_gt_u32_e64 s[56:57], s3, v4
	s_movk_i32 s3, 0x504
	v_cmp_gt_u32_e32 vcc, s3, v4
	v_cndmask_b32_e64 v0, 3, v0, s[56:57]
	s_nop 0
	v_cndmask_b32_e32 v2, 4, v0, vcc
	v_cmp_lt_i32_e64 s[58:59], 2, v2
	s_and_saveexec_b64 s[12:13], s[58:59]
	s_xor_b64 s[18:19], exec, s[12:13]
	s_cbranch_execz .LBB0_1097
	v_cmp_lt_i32_e64 s[58:59], 3, v2
	s_and_saveexec_b64 s[12:13], s[58:59]
	s_xor_b64 s[20:21], exec, s[12:13]
	s_or_saveexec_b64 s[22:23], s[20:21]
	s_mov_b64 s[20:21], 0
	v_mov_b32_e32 v0, 20
	s_xor_b64 exec, exec, s[22:23]
	s_mov_b64 s[20:21], exec
	v_mov_b32_e32 v0, 16
	s_or_b64 exec, exec, s[22:23]
